# phase loop: the next phase's kind/layer bytes are fetched before the grid barrier instead of after it (removes one exposed load round trip per phase)
# speedup vs baseline: 1.0116x; 1.0116x over previous
.LBB0_8:
	v_cmp_lt_i32_e32 vcc, s22, v235
	s_and_saveexec_b64 s[4:5], vcc
	s_cbranch_execz .LBB0_597
	s_add_u32 s48, s0, 0x1a8
	s_addc_u32 s49, s1, 0
	s_cmpk_lt_i32 s2, 0x100
	s_cselect_b64 s[4:5], -1, 0
	s_ashr_i32 s23, s2, 31
	s_lshr_b32 s3, s23, 29
	s_add_i32 s3, s2, s3
	v_writelane_b32 v254, s4, 0
	s_ashr_i32 s9, s3, 3
	s_and_b32 s3, s3, -8
	v_writelane_b32 v254, s5, 1
	s_sub_i32 s8, s2, s3
	s_and_b32 s4, s2, 7
	s_lshl_b32 s3, s8, 5
	v_writelane_b32 v254, s4, 2
	s_ashr_i32 s4, s2, 3
	s_cmpk_lt_i32 s2, 0x400
	v_writelane_b32 v254, s4, 3
	s_cselect_b64 s[4:5], -1, 0
	s_lshl_b32 s6, s8, 7
	v_writelane_b32 v254, s4, 4
	s_cmpk_lt_i32 s2, 0x800
	s_load_dwordx4 s[24:27], s[0:1], 0xa0
	v_writelane_b32 v254, s5, 5
	s_cselect_b64 s[4:5], -1, 0
	v_writelane_b32 v254, s4, 6
	s_lshl_b32 s10, s2, 3
	s_lshl_b32 s33, s2, 7
	v_writelane_b32 v254, s5, 7
	s_bfe_u32 s4, s2, 0x70003
	s_and_b32 s5, s10, 0xffffe000
	s_lshl_b32 s7, s4, 6
	s_or_b32 s5, s7, s5
	v_writelane_b32 v254, s5, 8
	s_and_b32 s7, s33, 0x380
	s_and_b32 s5, s2, 0xfffffc00
	s_or_b32 s5, s7, s5
	s_or_b32 s4, s5, s4
	s_ashr_i32 s5, s4, 31
	v_writelane_b32 v254, s7, 9
	s_lshl_b64 s[4:5], s[4:5], 15
	v_writelane_b32 v254, s4, 10
	s_mul_i32 s7, s8, 33
	v_lshrrev_b32_e32 v1, 20, v0
	v_writelane_b32 v254, s5, 11
	s_lshl_b32 s4, s2, 9
	v_writelane_b32 v254, s4, 12
	s_and_b32 s4, s10, 0xffffffc0
	v_writelane_b32 v254, s10, 13
	s_cmp_eq_u32 s2, 0
	v_writelane_b32 v254, s4, 14
	s_cselect_b64 s[4:5], -1, 0
	v_writelane_b32 v254, s4, 15
	s_cmpk_lt_i32 s2, 0x80
	v_lshrrev_b32_e32 v0, 10, v0
	v_writelane_b32 v254, s5, 16
	s_cselect_b64 s[4:5], -1, 0
	v_writelane_b32 v254, s4, 17
	s_cmpk_lt_i32 s2, 0x200
	s_cselect_b64 s[10:11], -1, 0
	v_writelane_b32 v254, s5, 18
	s_cmp_lt_i32 s8, 0
	s_cselect_b64 s[4:5], -1, 0
	v_writelane_b32 v254, s8, 19
	v_writelane_b32 v254, s4, 20
	s_mulk_i32 s8, 0x81
	v_or_b32_e32 v0, v0, v1
	v_writelane_b32 v254, s5, 21
	s_and_b64 s[4:5], s[4:5], exec
	s_cselect_b32 s3, s7, s3
	s_cselect_b32 s6, s8, s6
	s_add_i32 s3, s3, s9
	s_ashr_i32 s4, s3, 31
	s_lshr_b32 s4, s4, 27
	s_add_i32 s4, s3, s4
	s_ashr_i32 s5, s4, 5
	s_and_b32 s4, s4, 0xffe0
	s_sub_i32 s3, s3, s4
	s_bfe_i32 s4, s3, 0x80000
	s_bfe_u32 s4, s4, 0x3000c
	s_add_i32 s7, s3, s4
	s_bfe_i32 s4, s7, 0x80000
	s_and_b32 s7, s7, 0xf8
	s_sub_i32 s3, s3, s7
	s_lshl_b32 s5, s5, 3
	s_sext_i32_i8 s3, s3
	s_sext_i32_i16 s8, s4
	s_add_i32 s12, s5, s3
	s_ashr_i32 s3, s8, 3
	s_ashr_i32 s13, s12, 31
	s_lshr_b32 s4, s8, 3
	v_writelane_b32 v254, s3, 22
	s_lshl_b64 s[14:15], s[12:13], 19
	v_writelane_b32 v254, s14, 23
	s_bfe_i64 s[4:5], s[4:5], 0x100000
	s_mov_b32 s8, s12
	v_writelane_b32 v254, s15, 24
	s_lshl_b64 s[14:15], s[4:5], 19
	v_writelane_b32 v254, s14, 25
	s_lshl_b64 s[12:13], s[12:13], 21
	s_lshl_b64 s[4:5], s[4:5], 21
	v_writelane_b32 v254, s15, 26
	v_writelane_b32 v254, s8, 27
	s_add_i32 s3, s6, s9
	s_movk_i32 s58, 0x3ff
	v_writelane_b32 v254, s9, 28
	v_writelane_b32 v254, s12, 29
	v_and_or_b32 v0, v0, s58, v234
	v_mov_b32_e32 v209, 0
	v_writelane_b32 v254, s13, 30
	v_writelane_b32 v254, s4, 31
	v_writelane_b32 v255, s48, 0
	v_mbcnt_lo_u32_b32 v1, -1, 0
	v_writelane_b32 v254, s5, 32
	s_ashr_i32 s4, s3, 31
	s_lshr_b32 s4, s4, 25
	s_add_i32 s4, s3, s4
	s_ashr_i32 s5, s4, 7
	s_and_b32 s4, s4, 0xff80
	s_sub_i32 s3, s3, s4
	s_bfe_i32 s4, s3, 0x80000
	s_bfe_u32 s4, s4, 0x3000c
	s_add_i32 s6, s3, s4
	s_bfe_i32 s4, s6, 0x80000
	s_and_b32 s6, s6, 0xf8
	s_sub_i32 s3, s3, s6
	s_lshl_b32 s5, s5, 3
	s_sext_i32_i16 s7, s4
	s_sext_i32_i8 s3, s3
	v_writelane_b32 v254, s9, 33
	s_add_i32 s8, s5, s3
	s_ashr_i32 s3, s7, 3
	v_writelane_b32 v254, s3, 34
	s_mov_b32 s6, s8
	s_lshr_b32 s4, s7, 3
	s_ashr_i32 s9, s8, 31
	v_writelane_b32 v254, s6, 35
	s_bfe_i64 s[4:5], s[4:5], 0x100000
	s_lshl_b64 s[4:5], s[4:5], 19
	v_writelane_b32 v254, s7, 36
	s_lshl_b64 s[6:7], s[8:9], 19
	v_writelane_b32 v254, s6, 37
	s_waitcnt lgkmcnt(0)
	s_add_u32 s3, s26, 0xdc70000
	v_writelane_b32 v255, s49, 1
	v_writelane_b32 v254, s7, 38
	v_writelane_b32 v254, s4, 39
	v_mov_b32_e32 v236, 0x358637bd
	v_mov_b32_e32 v237, 0x2000
	v_writelane_b32 v254, s5, 40
	v_writelane_b32 v254, s3, 41
	s_addc_u32 s3, s27, 0
	s_add_u32 s4, s26, 0x100800
	v_writelane_b32 v254, s3, 42
	s_addc_u32 s5, s27, 0
	v_writelane_b32 v254, s4, 43
	s_lshl_b32 s3, s2, 10
	v_mov_b32_e32 v238, 1
	v_writelane_b32 v254, s5, 44
	v_writelane_b32 v254, s3, 45
	s_add_u32 s3, s26, 0x10000
	v_writelane_b32 v254, s3, 46
	s_addc_u32 s3, s27, 0
	v_writelane_b32 v254, s3, 47
	s_add_u32 s3, s26, 0x1c00400
	v_writelane_b32 v254, s3, 48
	s_addc_u32 s3, s27, 0
	v_writelane_b32 v254, s3, 49
	s_add_i32 s4, 0, 0x17800
	v_writelane_b32 v254, s4, 50
	s_add_i32 s4, 0, 0x1a800
	v_writelane_b32 v254, s4, 51
	s_add_i32 s4, 0, 0x8400
	v_writelane_b32 v254, s4, 52
	s_add_i32 s4, 0, 0x20004
	v_writelane_b32 v254, s4, 53
	v_cmp_gt_i32_e64 s[4:5], 0, v235
	s_mov_b32 s3, 0x800000
	v_mov_b32_e32 v239, 4
	v_writelane_b32 v254, s4, 54
	v_mov_b64_e32 v[252:253], 0x100
	v_mbcnt_hi_u32_b32 v240, -1, v1
	v_writelane_b32 v254, s5, 55
	v_cmp_eq_u32_e64 s[4:5], 0, v0
	v_mov_b32_e32 v241, 0x600
	v_mov_b64_e32 v[214:215], 0x10000
	v_writelane_b32 v254, s4, 56
	v_mov_b64_e32 v[216:217], 0x400
	v_mov_b64_e32 v[218:219], 0x3ff
	v_writelane_b32 v254, s5, 57
	v_cmp_eq_u32_e64 s[4:5], 0, v234
	v_mov_b32_e32 v242, 0x41b17218
	v_mov_b32_e32 v220, 0x3f317218
	v_writelane_b32 v254, s4, 58
	v_mov_b32_e32 v243, 0x7f800000
	v_mov_b32_e32 v244, 0x7fc00000
	v_writelane_b32 v254, s5, 59
	v_writelane_b32 v254, s10, 60
	s_xor_b64 s[4:5], s[10:11], -1
	v_mov_b32_e32 v245, 0xff800000
	v_writelane_b32 v254, s11, 61
	v_writelane_b32 v254, s4, 62
	s_movk_i32 s42, 0x210
	s_mov_b32 s43, 0xbfb8aa3b
	s_mov_b32 s44, 0x3f317217
	s_mov_b32 s45, 0x7f800000
	s_mov_b32 s20, 0xbc00000
	s_movk_i32 s59, 0x204
	s_mov_b32 s67, 0
	s_mov_b64 s[70:71], 0
	s_mov_b64 s[74:75], 0x40000
	s_mov_b64 s[76:77], 0x80
	s_mov_b64 s[78:79], 0x20000
	s_mov_b64 s[82:83], 0x50000
	s_mov_b64 s[84:85], 0x58000
	s_mov_b32 s60, 0x3e38aa3b
	v_writelane_b32 v254, s5, 63
	v_writelane_b32 v255, s33, 2
	s_ashr_i32 s4, s22, 31
	s_add_u32 s52, s0, s22
	s_addc_u32 s53, s1, s4
	global_load_ubyte v100, v209, s[52:53] offset:184
	global_load_ubyte v101, v209, s[52:53] offset:264
	s_branch .LBB0_13

.LBB0_13:
	v_mov_b32_e32 v222, v234
	s_mov_b64 s[54:55], 0
	s_mov_b32 s4, s67
	s_add_u32 s90, s26, s54
	v_readfirstlane_b32 s57, v222
	s_addc_u32 s91, s27, s55
	s_ashr_i32 s5, s4, 31
	s_ashr_i32 s56, s57, 6
	s_lshl_b64 s[4:5], s[4:5], 3
	s_add_u32 s94, s0, s4
	s_addc_u32 s95, s1, s5
	s_add_u32 s50, s90, 0x200000
	s_addc_u32 s51, s91, 0
	s_add_u32 s96, s90, 0xa00000
	s_addc_u32 s97, s91, 0
	s_add_u32 s92, s90, 0x1400000
	s_addc_u32 s93, s91, 0
	s_add_u32 s38, s90, 0x1c00000
	s_addc_u32 s39, s91, 0
	s_ashr_i32 s4, s22, 31
	s_add_u32 s52, s0, s22
	s_addc_u32 s53, s1, s4
	s_waitcnt vmcnt(0)
	v_mov_b32_e32 v0, v100
	v_mov_b32_e32 v1, v101
	s_waitcnt lgkmcnt(0)
	s_load_dword s6, s[48:49], 0x0
	v_and_b32_e32 v246, 63, v222
	s_waitcnt vmcnt(1)
	v_cmp_lt_i32_sdwa s[4:5], v0, v239 src0_sel:WORD_0 src1_sel:DWORD
	s_waitcnt vmcnt(0)
	v_readfirstlane_b32 s7, v1
	v_readfirstlane_b32 s73, v0
	s_bfe_i32 s72, s7, 0x80000
	s_and_b32 s7, s7, 15
	s_and_b64 vcc, exec, s[4:5]
	s_mov_b64 s[4:5], -1
	s_cbranch_vccnz .LBB0_329
	s_add_u32 s46, s90, 0x5c00000
	s_addc_u32 s47, s91, 0
	s_and_b32 s88, 0xffff, s73
	s_cmp_lt_i32 s88, 10
	s_cbranch_scc1 .LBB0_273
	s_cmp_lt_i32 s88, 12
	s_cbranch_scc1 .LBB0_255
	s_cmp_lt_i32 s88, 13
	s_cbranch_scc1 .LBB0_204
	s_cmp_lt_i32 s88, 15
	s_cbranch_scc0 .LBB0_203
	s_cmp_eq_u32 s88, 14
	s_cselect_b64 s[8:9], -1, 0
	s_cmp_lg_u32 s88, 14
	s_cselect_b64 s[4:5], -1, 0
	s_mov_b64 s[10:11], -1
	s_and_b64 vcc, exec, s[4:5]
	s_cbranch_vccz .LBB0_24
	s_and_b32 s10, 0xffff, s7
	s_lshl_b32 s12, s7, 10
	s_cmp_gt_u32 s10, 1
	s_mov_b64 s[10:11], -1
	s_cbranch_scc0 .LBB0_21
	s_load_dwordx2 s[10:11], s[94:95], 0x50
	s_lshl_b32 s13, s12, 2
	s_waitcnt lgkmcnt(0)
	s_add_u32 s10, s10, s13
	s_addc_u32 s11, s11, 0
	s_add_u32 s60, s10, 0xffffe000
	s_addc_u32 s61, s11, -1
	s_mov_b64 s[10:11], 0

.LBB0_533:
	s_add_i32 s22, s22, 1
	s_ashr_i32 s10, s22, 31
	s_add_u32 s12, s0, s22
	s_addc_u32 s13, s1, s10
	global_load_ubyte v100, v209, s[12:13] offset:184
	global_load_ubyte v101, v209, s[12:13] offset:264
	v_cmp_lt_i32_e32 vcc, s22, v235
	s_mov_b64 s[4:5], -1
	s_and_saveexec_b64 s[8:9], vcc
	s_cbranch_execz .LBB0_12
	s_mov_b64 s[4:5], exec
	v_readlane_b32 s10, v254, 54
	v_readlane_b32 s11, v254, 55
	s_and_b64 s[10:11], s[4:5], s[10:11]
	s_mov_b64 exec, s[10:11]
	s_cbranch_execz .LBB0_546
	v_readlane_b32 s10, v254, 56
	v_readlane_b32 s11, v254, 57
	s_waitcnt lgkmcnt(0)
	s_barrier
	s_barrier
	s_and_b64 exec, exec, s[10:11]
	s_cbranch_execz .LBB0_545
	buffer_wbl2 sc1
	s_waitcnt vmcnt(0)
	s_load_dwordx2 s[10:11], s[48:49], 0x58
	s_mov_b64 s[12:13], exec
	v_mbcnt_lo_u32_b32 v1, s12, 0
	v_mbcnt_hi_u32_b32 v1, s13, v1
	v_cmp_eq_u32_e32 vcc, 0, v1
	s_waitcnt lgkmcnt(0)
	global_load_dword v0, v209, s[10:11] offset:40
	s_and_saveexec_b64 s[14:15], vcc
	s_cbranch_execz .LBB0_538
	s_bcnt1_i32_b64 s7, s[12:13]
	v_mov_b32_e32 v2, s7
	global_atomic_add v2, v209, v2, s[10:11] offset:32 sc0
